# P0 weight transposes: touch-prefetch the 15 later row groups of each 64x64 tile before the depth-2 load pipeline
# speedup vs baseline: 1.0073x; 1.0028x over previous
.LBB0_47:
	s_andn2_saveexec_b64 s[38:39], s[38:39]
	s_cbranch_execz .LBB0_83
	v_and_b32_e32 v7, 31, v66
	v_lshlrev_b32_e32 v56, 6, v7
	v_and_b32_e32 v2, 0x1fc0, v97
	v_add_u32_e32 v58, 0xffffe800, v2
	v_mov_b32_e32 v59, v15
	v_or_b32_e32 v6, v56, v1
	v_lshl_add_u64 v[68:69], v[58:59], 2, v[18:19]
	v_lshlrev_b32_e32 v14, 13, v6
	v_lshl_add_u64 v[2:3], v[68:69], 0, v[14:15]
	s_mov_b32 s100, 0x8000
	s_mov_b32 s101, 0
	v_lshl_add_u64 v[160:161], v[2:3], 0, s[100:101]
	global_load_dword v162, v[160:161], off
	v_lshl_add_u64 v[160:161], v[160:161], 0, s[100:101]
	global_load_dword v163, v[160:161], off
	v_lshl_add_u64 v[160:161], v[160:161], 0, s[100:101]
	global_load_dword v164, v[160:161], off
	v_lshl_add_u64 v[160:161], v[160:161], 0, s[100:101]
	global_load_dword v165, v[160:161], off
	v_lshl_add_u64 v[160:161], v[160:161], 0, s[100:101]
	global_load_dword v166, v[160:161], off
	v_lshl_add_u64 v[160:161], v[160:161], 0, s[100:101]
	global_load_dword v167, v[160:161], off
	v_lshl_add_u64 v[160:161], v[160:161], 0, s[100:101]
	global_load_dword v168, v[160:161], off
	v_lshl_add_u64 v[160:161], v[160:161], 0, s[100:101]
	global_load_dword v169, v[160:161], off
	v_lshl_add_u64 v[160:161], v[160:161], 0, s[100:101]
	global_load_dword v170, v[160:161], off
	v_lshl_add_u64 v[160:161], v[160:161], 0, s[100:101]
	global_load_dword v171, v[160:161], off
	v_lshl_add_u64 v[160:161], v[160:161], 0, s[100:101]
	global_load_dword v172, v[160:161], off
	v_lshl_add_u64 v[160:161], v[160:161], 0, s[100:101]
	global_load_dword v173, v[160:161], off
	v_lshl_add_u64 v[160:161], v[160:161], 0, s[100:101]
	global_load_dword v174, v[160:161], off
	v_lshl_add_u64 v[160:161], v[160:161], 0, s[100:101]
	global_load_dword v175, v[160:161], off
	v_lshl_add_u64 v[160:161], v[160:161], 0, s[100:101]
	global_load_dword v176, v[160:161], off
	global_load_dwordx4 v[2:5], v[2:3], off
	v_readlane_b32 s64, v244, 0
	v_readlane_b32 s65, v244, 1
	v_readlane_b32 s66, v244, 2
	v_readlane_b32 s67, v244, 3
	s_mov_b64 s[40:41], s[64:65]
	s_mov_b64 s[42:43], s[66:67]
	v_mov_b32_e32 v8, s31
	v_mov_b32_e32 v9, s43
	v_cmp_gt_u32_e32 vcc, 16, v7
	v_mov_b32_e32 v7, s30
	v_mov_b32_e32 v10, 1.0
	v_cndmask_b32_e32 v61, v8, v9, vcc
	v_mov_b32_e32 v8, s42
	v_cndmask_b32_e32 v60, v7, v8, vcc
	v_cmp_ne_u64_e32 vcc, 0, v[60:61]
	v_mov_b32_e32 v12, 1.0
	v_readlane_b32 s68, v244, 4
	v_readlane_b32 s69, v244, 5
	v_readlane_b32 s70, v244, 6
	v_readlane_b32 s71, v244, 7
	s_and_saveexec_b64 s[40:41], vcc
	s_cbranch_execz .LBB0_50
	v_lshlrev_b32_e32 v14, 2, v6
	v_lshl_add_u64 v[6:7], v[60:61], 0, v[14:15]
	global_load_dword v12, v[6:7], off

.LBB0_95:
	s_or_b64 exec, exec, s[0:1]
	v_add_u32_e32 v3, 0x40000, v22
	v_and_b32_e32 v56, 0x7c0, v3
	v_ashrrev_i32_e32 v3, 31, v2
	v_lshl_add_u64 v[58:59], v[2:3], 2, v[20:21]
	v_or_b32_e32 v2, v56, v1
	v_mul_u32_u24_e32 v3, 0x1800, v2
	v_lshlrev_b32_e32 v14, 2, v3
	v_lshl_add_u64 v[4:5], v[58:59], 0, v[14:15]
	s_mov_b32 s100, 0x18000
	s_mov_b32 s101, 0
	v_lshl_add_u64 v[160:161], v[4:5], 0, s[100:101]
	global_load_dword v162, v[160:161], off
	v_lshl_add_u64 v[160:161], v[160:161], 0, s[100:101]
	global_load_dword v163, v[160:161], off
	v_lshl_add_u64 v[160:161], v[160:161], 0, s[100:101]
	global_load_dword v164, v[160:161], off
	v_lshl_add_u64 v[160:161], v[160:161], 0, s[100:101]
	global_load_dword v165, v[160:161], off
	v_lshl_add_u64 v[160:161], v[160:161], 0, s[100:101]
	global_load_dword v166, v[160:161], off
	v_lshl_add_u64 v[160:161], v[160:161], 0, s[100:101]
	global_load_dword v167, v[160:161], off
	v_lshl_add_u64 v[160:161], v[160:161], 0, s[100:101]
	global_load_dword v168, v[160:161], off
	v_lshl_add_u64 v[160:161], v[160:161], 0, s[100:101]
	global_load_dword v169, v[160:161], off
	v_lshl_add_u64 v[160:161], v[160:161], 0, s[100:101]
	global_load_dword v170, v[160:161], off
	v_lshl_add_u64 v[160:161], v[160:161], 0, s[100:101]
	global_load_dword v171, v[160:161], off
	v_lshl_add_u64 v[160:161], v[160:161], 0, s[100:101]
	global_load_dword v172, v[160:161], off
	v_lshl_add_u64 v[160:161], v[160:161], 0, s[100:101]
	global_load_dword v173, v[160:161], off
	v_lshl_add_u64 v[160:161], v[160:161], 0, s[100:101]
	global_load_dword v174, v[160:161], off
	v_lshl_add_u64 v[160:161], v[160:161], 0, s[100:101]
	global_load_dword v175, v[160:161], off
	v_lshl_add_u64 v[160:161], v[160:161], 0, s[100:101]
	global_load_dword v176, v[160:161], off
	global_load_dwordx4 v[6:9], v[4:5], off
	v_cndmask_b32_e64 v3, 0, 1, s[36:37]
	v_mov_b32_e32 v10, 1.0
	v_cmp_ne_u32_e64 s[0:1], 1, v3
	s_andn2_b64 vcc, exec, s[36:37]
	v_mov_b32_e32 v12, 1.0
	s_cbranch_vccnz .LBB0_97
	v_lshlrev_b32_e32 v2, 2, v2
	global_load_dword v12, v2, s[16:17]
